# prep S3b: right-hand-side LDS loads software-pipelined one group deep
# speedup vs baseline: 1.0437x; 1.0437x over previous
.LBB0_504:
	v_readlane_b32 s4, v252, 9
	v_readlane_b32 s5, v252, 10
	v_lshrrev_b32_e32 v3, 2, v81
	v_or_b32_e32 v70, s4, v64
	v_readlane_b32 s4, v252, 17
	v_and_b32_e32 v85, 12, v3
	s_movk_i32 s5, 0x104
	v_lshl_add_u32 v2, v70, 2, s4
	s_movk_i32 s4, 0xff
	v_bitop3_b32 v1, v3, s4, 12 bitop3:0x6c
	v_bitop3_b32 v90, v3, 63, 12 bitop3:0x6c
	v_lshl_add_u32 v68, v85, 2, s28
	v_mad_u32_u24 v0, v85, s5, v2
	v_lshl_add_u32 v4, v1, 2, s28
	v_mad_u32_u24 v6, v90, s5, v2
	ds_read_b32 v155, v68 offset:512
	ds_read_b32 v157, v0
	ds_read_b32 v154, v4
	ds_read_b32 v156, v6
	s_movk_i32 s4, 0x104
	v_xor_b32_e32 v0, 0x1ff, v85
	v_lshl_add_u32 v0, v0, 2, 0
	v_add_u32_e32 v0, 0x21a00, v0
	ds_read_b32 v159, v68 offset:1536
	ds_read_b32 v158, v0
	v_mul_u32_u24_e32 v0, 0x104, v85
	v_xor_b32_e32 v1, 62, v85
	v_add_u32_e32 v69, v0, v2
	v_xor_b32_e32 v0, 0xfe, v85
	v_lshl_add_u32 v0, v0, 2, s28
	v_mad_u32_u24 v4, v1, s4, v2
	ds_read_b32 v161, v68 offset:516
	ds_read_b32 v163, v69 offset:260
	ds_read_b32 v160, v0
	ds_read_b32 v162, v4
	v_xor_b32_e32 v1, 0x1fe, v85
	v_add_u32_e32 v0, 4, v68
	v_lshl_add_u32 v1, v1, 2, 0
	v_add_u32_e32 v4, 0x21a00, v1
	ds_read_b32 v165, v0 offset:1536
	ds_read_b32 v164, v4
	s_waitcnt lgkmcnt(6)
	v_pk_mul_f32 v[8:9], v[154:155], v[156:157]
	s_and_b64 vcc, exec, s[42:43]
	s_cbranch_vccnz .Lrl_0
	v_pk_mul_f32 v[8:9], v[8:9], v[158:159]
.Lrl_0:
	v_or_b32_e32 v93, 2, v85
	v_xor_b32_e32 v95, 61, v85
	v_lshl_add_u32 v0, v93, 2, s28
	v_xor_b32_e32 v1, 0xfd, v85
	v_mad_u32_u24 v6, v95, s4, v2
	v_lshl_add_u32 v1, v1, 2, s28
	ds_read_b32 v155, v0 offset:512
	ds_read_b32 v157, v69 offset:520
	ds_read_b32 v154, v1
	ds_read_b32 v156, v6
	v_xor_b32_e32 v1, 0x1fd, v85
	v_lshl_add_u32 v1, v1, 2, 0
	v_add_u32_e32 v4, 0x21a00, v1
	ds_read_b32 v159, v0 offset:1536
	ds_read_b32 v158, v4
	s_waitcnt lgkmcnt(6)
	v_pk_mul_f32 v[10:11], v[160:161], v[162:163]
	s_and_b64 vcc, exec, s[42:43]
	s_cbranch_vccnz .Lrl_1
	v_pk_mul_f32 v[10:11], v[10:11], v[164:165]
.Lrl_1:
	v_or_b32_e32 v1, 3, v3
	s_movk_i32 s4, 0xff
	v_bitop3_b32 v4, v3, 63, 3 bitop3:0x36
	v_lshl_add_u32 v0, v1, 2, s28
	v_mad_u32_u24 v6, v1, s5, v2
	v_bitop3_b32 v5, v3, s4, 3 bitop3:0x36
	v_lshl_add_u32 v14, v5, 2, s28
	v_mad_u32_u24 v15, v4, s5, v2
	ds_read_b32 v161, v0 offset:512
	ds_read_b32 v163, v6
	ds_read_b32 v160, v14
	ds_read_b32 v162, v15
	s_movk_i32 s4, 0x104
	v_xor_b32_e32 v1, 0x1ff, v1
	v_lshl_add_u32 v1, v1, 2, 0
	v_add_u32_e32 v4, 0x21a00, v1
	ds_read_b32 v165, v0 offset:1536
	ds_read_b32 v164, v4
	s_waitcnt lgkmcnt(6)
	v_pk_mul_f32 v[12:13], v[154:155], v[156:157]
	s_and_b64 vcc, exec, s[42:43]
	s_cbranch_vccnz .Lrl_2
	v_pk_mul_f32 v[12:13], v[12:13], v[158:159]
.Lrl_2:
	v_or_b32_e32 v88, 16, v85
	v_xor_b32_e32 v89, 47, v85
	v_lshl_add_u32 v0, v88, 2, s28
	v_xor_b32_e32 v1, 0xef, v85
	v_mad_u32_u24 v6, v89, s4, v2
	v_lshl_add_u32 v1, v1, 2, s28
	ds_read_b32 v155, v0 offset:512
	ds_read_b32 v157, v69 offset:4160
	ds_read_b32 v154, v1
	ds_read_b32 v156, v6
	v_xor_b32_e32 v1, 0x1ef, v85
	v_lshl_add_u32 v1, v1, 2, 0
	v_add_u32_e32 v4, 0x21a00, v1
	ds_read_b32 v159, v0 offset:1536
	ds_read_b32 v158, v4
	s_waitcnt lgkmcnt(6)
	v_pk_mul_f32 v[14:15], v[160:161], v[162:163]
	s_and_b64 vcc, exec, s[42:43]
	s_cbranch_vccnz .Lrl_3
	v_pk_mul_f32 v[14:15], v[14:15], v[164:165]
.Lrl_3:
	v_xor_b32_e32 v1, 0xee, v85
	v_xor_b32_e32 v0, 46, v85
	v_lshl_add_u32 v4, v1, 2, s28
	v_mad_u32_u24 v6, v0, s4, v2
	ds_read_b32 v161, v68 offset:580
	ds_read_b32 v163, v69 offset:4420
	ds_read_b32 v160, v4
	ds_read_b32 v162, v6
	v_xor_b32_e32 v1, 0x1ee, v85
	v_add_u32_e32 v0, 0x44, v68
	v_lshl_add_u32 v1, v1, 2, 0
	v_add_u32_e32 v4, 0x21a00, v1
	ds_read_b32 v165, v0 offset:1536
	ds_read_b32 v164, v4
	s_waitcnt lgkmcnt(6)
	v_pk_mul_f32 v[56:57], v[154:155], v[156:157]
	s_and_b64 vcc, exec, s[42:43]
	s_cbranch_vccnz .Lrl_4
	v_pk_mul_f32 v[56:57], v[56:57], v[158:159]
.Lrl_4:
	v_or_b32_e32 v91, 18, v85
	v_xor_b32_e32 v92, 45, v85
	v_lshl_add_u32 v0, v91, 2, s28
	v_xor_b32_e32 v1, 0xed, v85
	v_mad_u32_u24 v6, v92, s4, v2
	v_lshl_add_u32 v1, v1, 2, s28
	ds_read_b32 v155, v0 offset:512
	ds_read_b32 v157, v69 offset:4680
	ds_read_b32 v154, v1
	ds_read_b32 v156, v6
	v_xor_b32_e32 v1, 0x1ed, v85
	v_lshl_add_u32 v1, v1, 2, 0
	v_add_u32_e32 v4, 0x21a00, v1
	ds_read_b32 v159, v0 offset:1536
	ds_read_b32 v158, v4
	s_waitcnt lgkmcnt(6)
	v_pk_mul_f32 v[52:53], v[160:161], v[162:163]
	s_and_b64 vcc, exec, s[42:43]
	s_cbranch_vccnz .Lrl_5
	v_pk_mul_f32 v[52:53], v[52:53], v[164:165]
.Lrl_5:
	v_or_b32_e32 v1, 19, v3
	s_movk_i32 s4, 0xff
	v_bitop3_b32 v4, v3, 63, 19 bitop3:0x36
	v_lshl_add_u32 v0, v1, 2, s28
	v_mad_u32_u24 v6, v1, s5, v2
	v_bitop3_b32 v5, v3, s4, 19 bitop3:0x36
	v_lshl_add_u32 v54, v5, 2, s28
	v_mad_u32_u24 v55, v4, s5, v2
	ds_read_b32 v161, v0 offset:512
	ds_read_b32 v163, v6
	ds_read_b32 v160, v54
	ds_read_b32 v162, v55
	s_movk_i32 s4, 0x104
	v_xor_b32_e32 v1, 0x1ff, v1
	v_lshl_add_u32 v1, v1, 2, 0
	v_add_u32_e32 v4, 0x21a00, v1
	ds_read_b32 v165, v0 offset:1536
	ds_read_b32 v164, v4
	s_waitcnt lgkmcnt(6)
	v_pk_mul_f32 v[58:59], v[154:155], v[156:157]
	s_and_b64 vcc, exec, s[42:43]
	s_cbranch_vccnz .Lrl_6
	v_pk_mul_f32 v[58:59], v[58:59], v[158:159]
.Lrl_6:
	v_or_b32_e32 v76, 32, v85
	v_xor_b32_e32 v77, 31, v85
	v_lshl_add_u32 v0, v76, 2, s28
	v_xor_b32_e32 v1, 0xdf, v85
	v_mad_u32_u24 v6, v77, s4, v2
	v_lshl_add_u32 v1, v1, 2, s28
	ds_read_b32 v155, v0 offset:512
	ds_read_b32 v157, v69 offset:8320
	ds_read_b32 v154, v1
	ds_read_b32 v156, v6
	v_xor_b32_e32 v1, 0x1df, v85
	v_lshl_add_u32 v1, v1, 2, 0
	v_add_u32_e32 v4, 0x21a00, v1
	ds_read_b32 v159, v0 offset:1536
	ds_read_b32 v158, v4
	s_waitcnt lgkmcnt(6)
	v_pk_mul_f32 v[54:55], v[160:161], v[162:163]
	s_and_b64 vcc, exec, s[42:43]
	s_cbranch_vccnz .Lrl_7
	v_pk_mul_f32 v[54:55], v[54:55], v[164:165]
.Lrl_7:
	v_xor_b32_e32 v1, 0xde, v85
	v_xor_b32_e32 v0, 30, v85
	v_lshl_add_u32 v4, v1, 2, s28
	v_mad_u32_u24 v6, v0, s4, v2
	ds_read_b32 v161, v68 offset:644
	ds_read_b32 v163, v69 offset:8580
	ds_read_b32 v160, v4
	ds_read_b32 v162, v6
	v_xor_b32_e32 v1, 0x1de, v85
	v_add_u32_e32 v0, 0x84, v68
	v_lshl_add_u32 v1, v1, 2, 0
	v_add_u32_e32 v6, 0x21a00, v1
	ds_read_b32 v165, v0 offset:1536
	ds_read_b32 v164, v6
	s_waitcnt lgkmcnt(6)
	v_pk_mul_f32 v[60:61], v[154:155], v[156:157]
	s_and_b64 vcc, exec, s[42:43]
	s_cbranch_vccnz .Lrl_8
	v_pk_mul_f32 v[60:61], v[60:61], v[158:159]
.Lrl_8:
	v_or_b32_e32 v82, 34, v85
	v_xor_b32_e32 v84, 29, v85
	v_lshl_add_u32 v0, v82, 2, s28
	v_xor_b32_e32 v1, 0xdd, v85
	v_mad_u32_u24 v62, v84, s4, v2
	v_lshl_add_u32 v1, v1, 2, s28
	ds_read_b32 v155, v0 offset:512
	ds_read_b32 v157, v69 offset:8840
	ds_read_b32 v154, v1
	ds_read_b32 v156, v62
	v_xor_b32_e32 v1, 0x1dd, v85
	v_lshl_add_u32 v1, v1, 2, 0
	v_add_u32_e32 v6, 0x21a00, v1
	ds_read_b32 v159, v0 offset:1536
	ds_read_b32 v158, v6
	s_waitcnt lgkmcnt(6)
	v_pk_mul_f32 v[4:5], v[160:161], v[162:163]
	s_and_b64 vcc, exec, s[42:43]
	s_cbranch_vccnz .Lrl_9
	v_pk_mul_f32 v[4:5], v[4:5], v[164:165]
.Lrl_9:
	v_or_b32_e32 v1, 35, v3
	s_movk_i32 s4, 0xff
	v_bitop3_b32 v6, v3, 63, 35 bitop3:0x36
	v_lshl_add_u32 v0, v1, 2, s28
	v_mad_u32_u24 v66, v1, s5, v2
	v_bitop3_b32 v7, v3, s4, 35 bitop3:0x36
	v_lshl_add_u32 v71, v7, 2, s28
	v_mad_u32_u24 v72, v6, s5, v2
	ds_read_b32 v161, v0 offset:512
	ds_read_b32 v163, v66
	ds_read_b32 v160, v71
	ds_read_b32 v162, v72
	s_movk_i32 s4, 0x104
	v_xor_b32_e32 v1, 0x1ff, v1
	v_lshl_add_u32 v1, v1, 2, 0
	v_add_u32_e32 v66, 0x21a00, v1
	ds_read_b32 v165, v0 offset:1536
	ds_read_b32 v164, v66
	s_waitcnt lgkmcnt(6)
	v_pk_mul_f32 v[62:63], v[154:155], v[156:157]
	s_and_b64 vcc, exec, s[42:43]
	s_cbranch_vccnz .Lrl_10
	v_pk_mul_f32 v[62:63], v[62:63], v[158:159]
.Lrl_10:
	v_or_b32_e32 v72, 48, v85
	v_xor_b32_e32 v73, 15, v85
	v_lshl_add_u32 v0, v72, 2, s28
	v_xor_b32_e32 v1, 0xcf, v85
	v_lshl_add_u32 v1, v1, 2, s28
	v_mad_u32_u24 v71, v73, s4, v2
	ds_read_b32 v155, v0 offset:512
	ds_read_b32 v157, v69 offset:12480
	ds_read_b32 v154, v1
	ds_read_b32 v156, v71
	v_xor_b32_e32 v1, 0x1cf, v85
	v_lshl_add_u32 v1, v1, 2, 0
	v_add_u32_e32 v71, 0x21a00, v1
	ds_read_b32 v159, v0 offset:1536
	ds_read_b32 v158, v71
	s_waitcnt lgkmcnt(6)
	v_pk_mul_f32 v[6:7], v[160:161], v[162:163]
	s_and_b64 vcc, exec, s[42:43]
	s_cbranch_vccnz .Lrl_11
	v_pk_mul_f32 v[6:7], v[6:7], v[164:165]
.Lrl_11:
	v_xor_b32_e32 v0, 14, v85
	v_xor_b32_e32 v1, 0xce, v85
	v_mad_u32_u24 v74, v0, s4, v2
	v_lshl_add_u32 v71, v1, 2, s28
	ds_read_b32 v161, v68 offset:708
	ds_read_b32 v163, v69 offset:12740
	ds_read_b32 v160, v71
	ds_read_b32 v162, v74
	v_xor_b32_e32 v71, 0x1ce, v85
	v_add_u32_e32 v68, 0xc4, v68
	v_lshl_add_u32 v71, v71, 2, 0
	v_add_u32_e32 v71, 0x21a00, v71
	ds_read_b32 v165, v68 offset:1536
	ds_read_b32 v164, v71
	s_waitcnt lgkmcnt(6)
	v_pk_mul_f32 v[66:67], v[154:155], v[156:157]
	s_and_b64 vcc, exec, s[42:43]
	s_cbranch_vccnz .Lrl_12
	v_pk_mul_f32 v[66:67], v[66:67], v[158:159]
.Lrl_12:
	v_or_b32_e32 v74, 50, v85
	v_xor_b32_e32 v68, 0xcd, v85
	v_xor_b32_e32 v75, 13, v85
	v_lshl_add_u32 v71, v74, 2, s28
	v_lshl_add_u32 v68, v68, 2, s28
	v_mad_u32_u24 v83, v75, s4, v2
	ds_read_b32 v155, v71 offset:512
	ds_read_b32 v157, v69 offset:13000
	ds_read_b32 v154, v68
	ds_read_b32 v156, v83
	v_xor_b32_e32 v83, 0x1cd, v85
	v_lshl_add_u32 v83, v83, 2, 0
	v_add_u32_e32 v83, 0x21a00, v83
	ds_read_b32 v159, v71 offset:1536
	ds_read_b32 v158, v83
	s_waitcnt lgkmcnt(6)
	v_pk_mul_f32 v[0:1], v[160:161], v[162:163]
	s_and_b64 vcc, exec, s[42:43]
	s_cbranch_vccnz .Lrl_13
	v_pk_mul_f32 v[0:1], v[0:1], v[164:165]
.Lrl_13:
	v_or_b32_e32 v83, 51, v3
	v_bitop3_b32 v86, v3, 63, 51 bitop3:0x36
	s_movk_i32 s4, 0xff
	v_lshl_add_u32 v71, v83, 2, s28
	v_mad_u32_u24 v87, v83, s5, v2
	v_bitop3_b32 v3, v3, s4, 51 bitop3:0x36
	v_mad_u32_u24 v86, v86, s5, v2
	v_lshl_add_u32 v96, v3, 2, s28
	ds_read_b32 v161, v71 offset:512
	ds_read_b32 v163, v87
	ds_read_b32 v160, v96
	ds_read_b32 v162, v86
	v_xor_b32_e32 v83, 0x1ff, v83
	v_lshl_add_u32 v83, v83, 2, 0
	v_add_u32_e32 v83, 0x21a00, v83
	ds_read_b32 v165, v71 offset:1536
	ds_read_b32 v164, v83
	s_waitcnt lgkmcnt(6)
	v_pk_mul_f32 v[68:69], v[154:155], v[156:157]
	s_and_b64 vcc, exec, s[42:43]
	s_cbranch_vccnz .Lrl_14
	v_pk_mul_f32 v[68:69], v[68:69], v[158:159]
.Lrl_14:
	s_waitcnt lgkmcnt(0)
	v_pk_mul_f32 v[2:3], v[160:161], v[162:163]
	s_and_b64 vcc, exec, s[42:43]
	s_cbranch_vccnz .Lrl_15
	v_pk_mul_f32 v[2:3], v[2:3], v[164:165]
.Lrl_15:
.LBB0_536:
	v_lshlrev_b32_e32 v64, 8, v64
	v_lshlrev_b32_e32 v71, 2, v85
	v_add3_u32 v87, 0, v64, v71
	v_readlane_b32 s4, v252, 15
	ds_read_b128 v[96:99], v87 offset:51712
	s_add_u32 s36, s2, 0x8000
	v_add3_u32 v86, s4, v64, v71
	ds_read_b128 v[100:103], v86
	s_addc_u32 s37, s3, 0
	v_lshlrev_b32_e32 v83, 1, v70
	v_readlane_b32 s4, v254, 57
	s_waitcnt lgkmcnt(1)
	v_mfma_f32_16x16x4_f32 v[104:107], v96, v9, 0
	s_add_u32 s28, s2, 0xe000
	v_add_u32_e32 v64, s4, v83
	s_addc_u32 s29, s3, 0
	s_mov_b64 s[44:45], -1
	s_and_b64 vcc, exec, s[42:43]
	s_waitcnt lgkmcnt(0)
	v_mfma_f32_16x16x4_f32 v[108:111], v100, v8, 0
	v_mfma_f32_16x16x4_f32 v[104:107], v97, v11, v[104:107]
	v_mfma_f32_16x16x4_f32 v[8:11], v101, v10, v[108:111]
	v_mfma_f32_16x16x4_f32 v[104:107], v98, v13, v[104:107]
	v_mfma_f32_16x16x4_f32 v[108:111], v102, v12, v[8:11]
	v_mfma_f32_16x16x4_f32 v[8:11], v99, v15, v[104:107]
	v_mfma_f32_16x16x4_f32 v[12:15], v103, v14, v[108:111]
	s_nop 8
	v_cvt_pk_bf16_f32 v70, v8, v9
	v_cvt_pk_bf16_f32 v71, v10, v11
	s_cbranch_vccnz .LBB0_538
	v_mul_u32_u24_e32 v97, 0x110, v85
	v_readlane_b32 s4, v254, 58
	v_sub_u32_e32 v85, 62, v85
	v_cvt_pk_bf16_f32 v96, v12, v13
	v_add3_u32 v97, s4, v97, v83
	s_movk_i32 s4, 0x110
	v_mad_u32_u24 v90, v90, s4, v64
	v_mad_u32_u24 v85, v85, s4, v64
	ds_write_b16 v97, v70
	ds_write_b16_d16_hi v97, v70 offset:272
	ds_write_b16 v90, v96
	ds_write_b16_d16_hi v85, v96
	v_cvt_pk_bf16_f32 v85, v14, v15
	v_mad_u32_u24 v90, v95, s4, v64
	ds_write_b16 v97, v71 offset:544
	ds_write_b16_d16_hi v97, v71 offset:816
	ds_write_b16 v90, v85
	v_sub_u32_e32 v90, 62, v93
	v_mad_u32_u24 v90, v90, s4, v64
	s_mov_b64 s[44:45], 0
	ds_write_b16_d16_hi v90, v85
